# lever 9 loop-edge: GEMM K-loops do their scalar pointer/counter/exit-test block in front of the loop-back barrier instead of behind it (4 loops)
# speedup vs baseline: 1.0016x; 1.0016x over previous
.LBB0_540:
	s_add_u32 s22, s18, s20
	s_addc_u32 s23, s19, s21
	s_add_u32 s22, s22, 0x100
	s_addc_u32 s23, s23, 0
	s_add_u32 s49, s40, s20
	s_addc_u32 s56, s41, s21
	s_add_i32 s58, 0, 0x10000
	s_cmpk_eq_i32 s20, 0x700
	s_cselect_b32 s23, s15, s23
	s_cselect_b32 s22, s14, s22
	v_add_u32_e32 v149, s58, v147
	s_cselect_b32 s57, s17, s56
	s_cselect_b32 s56, s16, s49
	s_add_i32 s49, 0, 0x14000
	ds_read_b128 v[150:153], v149
	ds_read_b128 v[154:157], v149 offset:1024
	ds_read_b128 v[158:161], v149 offset:2048
	ds_read_b128 v[162:165], v149 offset:3072
	v_add_u32_e32 v149, s49, v147
	ds_read_b128 v[166:169], v149
	ds_read_b128 v[170:173], v149 offset:1024
	ds_read_b128 v[174:177], v149 offset:2048
	ds_read_b128 v[178:181], v149 offset:3072
	v_lshl_add_u64 v[220:221], v[142:143], 0, s[20:21]
	s_add_i32 m0, s27, 0xc000
	ds_read_b128 v[182:185], v148
	ds_read_b128 v[186:189], v148 offset:1024
	ds_read_b128 v[204:207], v148 offset:2048
	ds_read_b128 v[208:211], v148 offset:3072
	ds_read_b128 v[212:215], v148 offset:4096
	ds_read_b128 v[216:219], v148 offset:5120
	ds_read_b128 v[230:233], v148 offset:6144
	ds_read_b128 v[234:237], v148 offset:7168
	global_load_lds_dwordx4 v[220:221], off
	v_lshl_add_u64 v[220:221], v[144:145], 0, s[20:21]
	s_add_i32 m0, s27, 0xe000
	s_nop 0
	global_load_lds_dwordx4 v[220:221], off
	s_waitcnt vmcnt(8)
	s_waitcnt lgkmcnt(0)
	s_barrier
	s_setprio 1
	s_waitcnt lgkmcnt(0)
	v_mfma_f32_16x16x32_bf16 v[126:129], v[150:153], v[182:185], v[126:129]
	v_mfma_f32_16x16x32_bf16 v[118:121], v[158:161], v[182:185], v[118:121]
	v_mfma_f32_16x16x32_bf16 v[110:113], v[150:153], v[204:207], v[110:113]
	v_mfma_f32_16x16x32_bf16 v[102:105], v[158:161], v[204:207], v[102:105]
	v_mfma_f32_16x16x32_bf16 v[94:97], v[150:153], v[212:215], v[94:97]
	v_mfma_f32_16x16x32_bf16 v[86:89], v[158:161], v[212:215], v[86:89]
	v_mfma_f32_16x16x32_bf16 v[78:81], v[150:153], v[230:233], v[78:81]
	v_mfma_f32_16x16x32_bf16 v[70:73], v[158:161], v[230:233], v[70:73]
	v_mfma_f32_16x16x32_bf16 v[126:129], v[154:157], v[186:189], v[126:129]
	v_mfma_f32_16x16x32_bf16 v[118:121], v[162:165], v[186:189], v[118:121]
	v_mfma_f32_16x16x32_bf16 v[110:113], v[154:157], v[208:211], v[110:113]
	v_mfma_f32_16x16x32_bf16 v[102:105], v[162:165], v[208:211], v[102:105]
	v_mfma_f32_16x16x32_bf16 v[94:97], v[154:157], v[216:219], v[94:97]
	v_mfma_f32_16x16x32_bf16 v[86:89], v[162:165], v[216:219], v[86:89]
	v_mfma_f32_16x16x32_bf16 v[78:81], v[154:157], v[234:237], v[78:81]
	v_mfma_f32_16x16x32_bf16 v[70:73], v[162:165], v[234:237], v[70:73]
	s_setprio 0
	s_setprio 1
	v_mfma_f32_16x16x32_bf16 v[122:125], v[166:169], v[182:185], v[122:125]
	v_mfma_f32_16x16x32_bf16 v[114:117], v[174:177], v[182:185], v[114:117]
	v_mfma_f32_16x16x32_bf16 v[106:109], v[166:169], v[204:207], v[106:109]
	v_mfma_f32_16x16x32_bf16 v[98:101], v[174:177], v[204:207], v[98:101]
	v_mfma_f32_16x16x32_bf16 v[90:93], v[166:169], v[212:215], v[90:93]
	v_mfma_f32_16x16x32_bf16 v[82:85], v[174:177], v[212:215], v[82:85]
	v_mfma_f32_16x16x32_bf16 v[74:77], v[166:169], v[230:233], v[74:77]
	v_mfma_f32_16x16x32_bf16 v[66:69], v[174:177], v[230:233], v[66:69]
	v_mfma_f32_16x16x32_bf16 v[122:125], v[170:173], v[186:189], v[122:125]
	v_mfma_f32_16x16x32_bf16 v[114:117], v[178:181], v[186:189], v[114:117]
	v_mfma_f32_16x16x32_bf16 v[106:109], v[170:173], v[208:211], v[106:109]
	v_mfma_f32_16x16x32_bf16 v[98:101], v[178:181], v[208:211], v[98:101]
	v_mfma_f32_16x16x32_bf16 v[90:93], v[170:173], v[216:219], v[90:93]
	v_mfma_f32_16x16x32_bf16 v[82:85], v[178:181], v[216:219], v[82:85]
	v_mfma_f32_16x16x32_bf16 v[74:77], v[170:173], v[234:237], v[74:77]
	v_mfma_f32_16x16x32_bf16 v[66:69], v[178:181], v[234:237], v[66:69]
	s_setprio 0
	s_barrier
	s_add_i32 s58, s58, s25
	v_lshl_add_u64 v[220:221], s[56:57], 0, v[134:135]
	s_mov_b32 m0, s58
	ds_read_b128 v[182:185], v148 offset:16384
	ds_read_b128 v[186:189], v148 offset:17408
	ds_read_b128 v[204:207], v148 offset:18432
	ds_read_b128 v[208:211], v148 offset:19456
	ds_read_b128 v[212:215], v148 offset:20480
	ds_read_b128 v[216:219], v148 offset:21504
	ds_read_b128 v[230:233], v148 offset:22528
	ds_read_b128 v[234:237], v148 offset:23552
	global_load_lds_dwordx4 v[220:221], off
	s_add_i32 m0, s58, 0x2000
	v_lshl_add_u64 v[238:239], s[56:57], 0, v[130:131]
	s_add_u32 s56, s56, s4
	s_addc_u32 s57, s57, s5
	s_add_i32 s49, s49, s25
	global_load_lds_dwordx4 v[238:239], off
	v_lshl_add_u64 v[240:241], s[56:57], 0, v[134:135]
	s_mov_b32 m0, s49
	v_lshl_add_u64 v[242:243], s[56:57], 0, v[130:131]
	global_load_lds_dwordx4 v[240:241], off
	s_add_i32 m0, s49, 0x2000
	v_lshl_add_u64 v[244:245], s[22:23], 0, v[136:137]
	global_load_lds_dwordx4 v[242:243], off
	s_mov_b32 m0, s27
	v_lshl_add_u64 v[246:247], s[22:23], 0, v[132:133]
	global_load_lds_dwordx4 v[244:245], off
	s_mov_b32 m0, s28
	s_nop 0
	global_load_lds_dwordx4 v[246:247], off
	s_waitcnt vmcnt(8)
	s_waitcnt lgkmcnt(0)
	s_barrier
	s_setprio 1
	s_waitcnt lgkmcnt(0)
	v_mfma_f32_16x16x32_bf16 v[62:65], v[150:153], v[182:185], v[62:65]
	v_mfma_f32_16x16x32_bf16 v[54:57], v[158:161], v[182:185], v[54:57]
	v_mfma_f32_16x16x32_bf16 v[46:49], v[150:153], v[204:207], v[46:49]
	v_mfma_f32_16x16x32_bf16 v[38:41], v[158:161], v[204:207], v[38:41]
	v_mfma_f32_16x16x32_bf16 v[30:33], v[150:153], v[212:215], v[30:33]
	v_mfma_f32_16x16x32_bf16 v[22:25], v[158:161], v[212:215], v[22:25]
	v_mfma_f32_16x16x32_bf16 v[14:17], v[150:153], v[230:233], v[14:17]
	v_mfma_f32_16x16x32_bf16 v[6:9], v[158:161], v[230:233], v[6:9]
	v_mfma_f32_16x16x32_bf16 v[62:65], v[154:157], v[186:189], v[62:65]
	v_mfma_f32_16x16x32_bf16 v[54:57], v[162:165], v[186:189], v[54:57]
	v_mfma_f32_16x16x32_bf16 v[46:49], v[154:157], v[208:211], v[46:49]
	v_mfma_f32_16x16x32_bf16 v[38:41], v[162:165], v[208:211], v[38:41]
	v_mfma_f32_16x16x32_bf16 v[30:33], v[154:157], v[216:219], v[30:33]
	v_mfma_f32_16x16x32_bf16 v[22:25], v[162:165], v[216:219], v[22:25]
	v_mfma_f32_16x16x32_bf16 v[14:17], v[154:157], v[234:237], v[14:17]
	v_mfma_f32_16x16x32_bf16 v[6:9], v[162:165], v[234:237], v[6:9]
	s_setprio 0
	s_setprio 1
	v_mfma_f32_16x16x32_bf16 v[58:61], v[166:169], v[182:185], v[58:61]
	v_mfma_f32_16x16x32_bf16 v[50:53], v[174:177], v[182:185], v[50:53]
	v_mfma_f32_16x16x32_bf16 v[42:45], v[166:169], v[204:207], v[42:45]
	v_mfma_f32_16x16x32_bf16 v[34:37], v[174:177], v[204:207], v[34:37]
	v_mfma_f32_16x16x32_bf16 v[26:29], v[166:169], v[212:215], v[26:29]
	v_mfma_f32_16x16x32_bf16 v[18:21], v[174:177], v[212:215], v[18:21]
	v_mfma_f32_16x16x32_bf16 v[10:13], v[166:169], v[230:233], v[10:13]
	v_mfma_f32_16x16x32_bf16 v[2:5], v[174:177], v[230:233], v[2:5]
	v_mfma_f32_16x16x32_bf16 v[58:61], v[170:173], v[186:189], v[58:61]
	v_mfma_f32_16x16x32_bf16 v[50:53], v[178:181], v[186:189], v[50:53]
	v_mfma_f32_16x16x32_bf16 v[42:45], v[170:173], v[208:211], v[42:45]
	v_mfma_f32_16x16x32_bf16 v[34:37], v[178:181], v[208:211], v[34:37]
	v_mfma_f32_16x16x32_bf16 v[26:29], v[170:173], v[216:219], v[26:29]
	v_mfma_f32_16x16x32_bf16 v[18:21], v[178:181], v[216:219], v[18:21]
	v_mfma_f32_16x16x32_bf16 v[10:13], v[170:173], v[234:237], v[10:13]
	v_mfma_f32_16x16x32_bf16 v[2:5], v[178:181], v[234:237], v[2:5]
	s_setprio 0
	s_barrier
	s_add_i32 s49, 0, 0x18000
	v_add_u32_e32 v149, s49, v147
	s_add_i32 s56, 0, 0x1c000
	ds_read_b128 v[150:153], v149
	ds_read_b128 v[154:157], v149 offset:1024
	ds_read_b128 v[158:161], v149 offset:2048
	ds_read_b128 v[162:165], v149 offset:3072
	v_add_u32_e32 v149, s56, v147
	ds_read_b128 v[166:169], v149
	ds_read_b128 v[170:173], v149 offset:1024
	ds_read_b128 v[174:177], v149 offset:2048
	ds_read_b128 v[178:181], v149 offset:3072
	s_add_u32 s22, s22, s4
	s_addc_u32 s23, s23, s5
	s_mov_b32 m0, s29
	v_lshl_add_u64 v[248:249], s[22:23], 0, v[136:137]
	ds_read_b128 v[182:185], v148 offset:32768
	ds_read_b128 v[186:189], v148 offset:33792
	ds_read_b128 v[204:207], v148 offset:34816
	ds_read_b128 v[208:211], v148 offset:35840
	ds_read_b128 v[212:215], v148 offset:36864
	ds_read_b128 v[216:219], v148 offset:37888
	ds_read_b128 v[230:233], v148 offset:38912
	ds_read_b128 v[234:237], v148 offset:39936
	global_load_lds_dwordx4 v[248:249], off
	v_lshl_add_u64 v[248:249], s[22:23], 0, v[132:133]
	s_mov_b32 m0, s30
	s_nop 0
	global_load_lds_dwordx4 v[248:249], off
	s_waitcnt vmcnt(8)
	s_waitcnt lgkmcnt(0)
	s_barrier
	s_setprio 1
	s_waitcnt lgkmcnt(0)
	v_mfma_f32_16x16x32_bf16 v[126:129], v[150:153], v[182:185], v[126:129]
	v_mfma_f32_16x16x32_bf16 v[118:121], v[158:161], v[182:185], v[118:121]
	v_mfma_f32_16x16x32_bf16 v[110:113], v[150:153], v[204:207], v[110:113]
	v_mfma_f32_16x16x32_bf16 v[102:105], v[158:161], v[204:207], v[102:105]
	v_mfma_f32_16x16x32_bf16 v[94:97], v[150:153], v[212:215], v[94:97]
	v_mfma_f32_16x16x32_bf16 v[86:89], v[158:161], v[212:215], v[86:89]
	v_mfma_f32_16x16x32_bf16 v[78:81], v[150:153], v[230:233], v[78:81]
	v_mfma_f32_16x16x32_bf16 v[70:73], v[158:161], v[230:233], v[70:73]
	v_mfma_f32_16x16x32_bf16 v[126:129], v[154:157], v[186:189], v[126:129]
	v_mfma_f32_16x16x32_bf16 v[118:121], v[162:165], v[186:189], v[118:121]
	v_mfma_f32_16x16x32_bf16 v[110:113], v[154:157], v[208:211], v[110:113]
	v_mfma_f32_16x16x32_bf16 v[102:105], v[162:165], v[208:211], v[102:105]
	v_mfma_f32_16x16x32_bf16 v[94:97], v[154:157], v[216:219], v[94:97]
	v_mfma_f32_16x16x32_bf16 v[86:89], v[162:165], v[216:219], v[86:89]
	v_mfma_f32_16x16x32_bf16 v[78:81], v[154:157], v[234:237], v[78:81]
	v_mfma_f32_16x16x32_bf16 v[70:73], v[162:165], v[234:237], v[70:73]
	s_setprio 0
	s_setprio 1
	v_mfma_f32_16x16x32_bf16 v[122:125], v[166:169], v[182:185], v[122:125]
	v_mfma_f32_16x16x32_bf16 v[114:117], v[174:177], v[182:185], v[114:117]
	v_mfma_f32_16x16x32_bf16 v[106:109], v[166:169], v[204:207], v[106:109]
	v_mfma_f32_16x16x32_bf16 v[98:101], v[174:177], v[204:207], v[98:101]
	v_mfma_f32_16x16x32_bf16 v[90:93], v[166:169], v[212:215], v[90:93]
	v_mfma_f32_16x16x32_bf16 v[82:85], v[174:177], v[212:215], v[82:85]
	v_mfma_f32_16x16x32_bf16 v[74:77], v[166:169], v[230:233], v[74:77]
	v_mfma_f32_16x16x32_bf16 v[66:69], v[174:177], v[230:233], v[66:69]
	v_mfma_f32_16x16x32_bf16 v[122:125], v[170:173], v[186:189], v[122:125]
	v_mfma_f32_16x16x32_bf16 v[114:117], v[178:181], v[186:189], v[114:117]
	v_mfma_f32_16x16x32_bf16 v[106:109], v[170:173], v[208:211], v[106:109]
	v_mfma_f32_16x16x32_bf16 v[98:101], v[178:181], v[208:211], v[98:101]
	v_mfma_f32_16x16x32_bf16 v[90:93], v[170:173], v[216:219], v[90:93]
	v_mfma_f32_16x16x32_bf16 v[82:85], v[178:181], v[216:219], v[82:85]
	v_mfma_f32_16x16x32_bf16 v[74:77], v[170:173], v[234:237], v[74:77]
	v_mfma_f32_16x16x32_bf16 v[66:69], v[178:181], v[234:237], v[66:69]
	s_setprio 0
	s_barrier
	s_add_i32 s22, s49, s25
	v_lshl_add_u64 v[220:221], v[220:221], 0, s[68:69]
	s_mov_b32 m0, s22
	ds_read_b128 v[182:185], v148 offset:49152
	ds_read_b128 v[186:189], v148 offset:50176
	ds_read_b128 v[204:207], v148 offset:51200
	ds_read_b128 v[208:211], v148 offset:52224
	ds_read_b128 v[212:215], v148 offset:53248
	ds_read_b128 v[216:219], v148 offset:54272
	ds_read_b128 v[230:233], v148 offset:55296
	ds_read_b128 v[234:237], v148 offset:56320
	global_load_lds_dwordx4 v[220:221], off
	v_lshl_add_u64 v[220:221], v[238:239], 0, s[68:69]
	s_add_i32 m0, s22, 0x2000
	s_add_i32 s22, s56, s25
	global_load_lds_dwordx4 v[220:221], off
	v_lshl_add_u64 v[220:221], v[240:241], 0, s[68:69]
	s_mov_b32 m0, s22
	s_nop 0
	global_load_lds_dwordx4 v[220:221], off
	v_lshl_add_u64 v[220:221], v[242:243], 0, s[68:69]
	s_add_i32 m0, s22, 0x2000
	s_nop 0
	global_load_lds_dwordx4 v[220:221], off
	v_lshl_add_u64 v[220:221], v[244:245], 0, s[68:69]
	s_mov_b32 m0, s31
	s_nop 0
	global_load_lds_dwordx4 v[220:221], off
	v_lshl_add_u64 v[220:221], v[246:247], 0, s[68:69]
	s_mov_b32 m0, s33
	s_nop 0
	global_load_lds_dwordx4 v[220:221], off
	s_waitcnt vmcnt(8)
	s_waitcnt lgkmcnt(0)
	s_barrier
	s_setprio 1
	s_waitcnt lgkmcnt(0)
	v_mfma_f32_16x16x32_bf16 v[62:65], v[150:153], v[182:185], v[62:65]
	v_mfma_f32_16x16x32_bf16 v[54:57], v[158:161], v[182:185], v[54:57]
	v_mfma_f32_16x16x32_bf16 v[46:49], v[150:153], v[204:207], v[46:49]
	v_mfma_f32_16x16x32_bf16 v[38:41], v[158:161], v[204:207], v[38:41]
	v_mfma_f32_16x16x32_bf16 v[30:33], v[150:153], v[212:215], v[30:33]
	v_mfma_f32_16x16x32_bf16 v[22:25], v[158:161], v[212:215], v[22:25]
	v_mfma_f32_16x16x32_bf16 v[14:17], v[150:153], v[230:233], v[14:17]
	v_mfma_f32_16x16x32_bf16 v[6:9], v[158:161], v[230:233], v[6:9]
	v_mfma_f32_16x16x32_bf16 v[62:65], v[154:157], v[186:189], v[62:65]
	v_mfma_f32_16x16x32_bf16 v[54:57], v[162:165], v[186:189], v[54:57]
	v_mfma_f32_16x16x32_bf16 v[46:49], v[154:157], v[208:211], v[46:49]
	v_mfma_f32_16x16x32_bf16 v[38:41], v[162:165], v[208:211], v[38:41]
	v_mfma_f32_16x16x32_bf16 v[30:33], v[154:157], v[216:219], v[30:33]
	v_mfma_f32_16x16x32_bf16 v[22:25], v[162:165], v[216:219], v[22:25]
	v_mfma_f32_16x16x32_bf16 v[14:17], v[154:157], v[234:237], v[14:17]
	v_mfma_f32_16x16x32_bf16 v[6:9], v[162:165], v[234:237], v[6:9]
	s_setprio 0
	s_setprio 1
	v_mfma_f32_16x16x32_bf16 v[58:61], v[166:169], v[182:185], v[58:61]
	v_mfma_f32_16x16x32_bf16 v[50:53], v[174:177], v[182:185], v[50:53]
	v_mfma_f32_16x16x32_bf16 v[42:45], v[166:169], v[204:207], v[42:45]
	v_mfma_f32_16x16x32_bf16 v[34:37], v[174:177], v[204:207], v[34:37]
	v_mfma_f32_16x16x32_bf16 v[26:29], v[166:169], v[212:215], v[26:29]
	v_mfma_f32_16x16x32_bf16 v[18:21], v[174:177], v[212:215], v[18:21]
	v_mfma_f32_16x16x32_bf16 v[10:13], v[166:169], v[230:233], v[10:13]
	v_mfma_f32_16x16x32_bf16 v[2:5], v[174:177], v[230:233], v[2:5]
	v_mfma_f32_16x16x32_bf16 v[58:61], v[170:173], v[186:189], v[58:61]
	v_mfma_f32_16x16x32_bf16 v[50:53], v[178:181], v[186:189], v[50:53]
	v_mfma_f32_16x16x32_bf16 v[42:45], v[170:173], v[208:211], v[42:45]
	v_mfma_f32_16x16x32_bf16 v[34:37], v[178:181], v[208:211], v[34:37]
	v_mfma_f32_16x16x32_bf16 v[26:29], v[170:173], v[216:219], v[26:29]
	v_mfma_f32_16x16x32_bf16 v[18:21], v[178:181], v[216:219], v[18:21]
	v_mfma_f32_16x16x32_bf16 v[10:13], v[170:173], v[234:237], v[10:13]
	v_mfma_f32_16x16x32_bf16 v[2:5], v[178:181], v[234:237], v[2:5]
	s_setprio 0
	s_add_i32 s48, s48, 2
	s_add_u32 s20, s20, 0x100
	s_addc_u32 s21, s21, 0
	s_cmp_gt_u32 s48, 13
	s_barrier
	s_cbranch_scc0 .LBB0_540
	s_and_b64 vcc, exec, s[12:13]
	s_cbranch_vccz .LBB0_543
	s_barrier

.LBB0_590:
	s_add_i32 s86, s26, 2
	s_add_u32 s74, s24, 0x80
	s_addc_u32 s27, s25, 0
	s_add_i32 s87, 0, 0x10000
	s_cmp_eq_u32 s19, s26
	s_cselect_b32 s27, s21, s27
	s_cselect_b32 s26, s20, s74
	v_add_u32_e32 v148, s87, v152
	s_cselect_b32 s75, s23, s29
	s_cselect_b32 s74, s22, s28
	s_add_i32 s88, 0, 0x14000
	ds_read_b128 v[130:133], v148
	ds_read_b128 v[144:147], v148 offset:1024
	ds_read_b128 v[154:157], v148 offset:2048
	ds_read_b128 v[158:161], v148 offset:3072
	v_add_u32_e32 v148, s88, v152
	ds_read_b128 v[162:165], v148
	ds_read_b128 v[166:169], v148 offset:1024
	ds_read_b128 v[170:173], v148 offset:2048
	ds_read_b128 v[174:177], v148 offset:3072
	v_lshl_add_u64 v[148:149], s[24:25], 0, v[140:141]
	s_add_i32 m0, s34, 0xc000
	ds_read_b128 v[178:181], v153
	ds_read_b128 v[182:185], v153 offset:1024
	ds_read_b128 v[186:189], v153 offset:2048
	ds_read_b128 v[204:207], v153 offset:3072
	ds_read_b128 v[208:211], v153 offset:4096
	ds_read_b128 v[212:215], v153 offset:5120
	ds_read_b128 v[216:219], v153 offset:6144
	ds_read_b128 v[230:233], v153 offset:7168
	global_load_lds_dwordx4 v[148:149], off
	v_lshl_add_u64 v[148:149], s[24:25], 0, v[142:143]
	s_add_i32 m0, s34, 0xe000
	s_nop 0
	global_load_lds_dwordx4 v[148:149], off
	s_waitcnt vmcnt(8)
	s_waitcnt lgkmcnt(0)
	s_barrier
	s_setprio 1
	s_waitcnt lgkmcnt(0)
	v_mfma_f32_16x16x32_bf16 v[126:129], v[130:133], v[178:181], v[126:129]
	v_mfma_f32_16x16x32_bf16 v[122:125], v[154:157], v[178:181], v[122:125]
	v_mfma_f32_16x16x32_bf16 v[110:113], v[130:133], v[186:189], v[110:113]
	v_mfma_f32_16x16x32_bf16 v[106:109], v[154:157], v[186:189], v[106:109]
	v_mfma_f32_16x16x32_bf16 v[94:97], v[130:133], v[208:211], v[94:97]
	v_mfma_f32_16x16x32_bf16 v[90:93], v[154:157], v[208:211], v[90:93]
	v_mfma_f32_16x16x32_bf16 v[78:81], v[130:133], v[216:219], v[78:81]
	v_mfma_f32_16x16x32_bf16 v[74:77], v[154:157], v[216:219], v[74:77]
	v_mfma_f32_16x16x32_bf16 v[126:129], v[144:147], v[182:185], v[126:129]
	v_mfma_f32_16x16x32_bf16 v[122:125], v[158:161], v[182:185], v[122:125]
	v_mfma_f32_16x16x32_bf16 v[110:113], v[144:147], v[204:207], v[110:113]
	v_mfma_f32_16x16x32_bf16 v[106:109], v[158:161], v[204:207], v[106:109]
	v_mfma_f32_16x16x32_bf16 v[94:97], v[144:147], v[212:215], v[94:97]
	v_mfma_f32_16x16x32_bf16 v[90:93], v[158:161], v[212:215], v[90:93]
	v_mfma_f32_16x16x32_bf16 v[78:81], v[144:147], v[230:233], v[78:81]
	v_mfma_f32_16x16x32_bf16 v[74:77], v[158:161], v[230:233], v[74:77]
	s_setprio 0
	s_setprio 1
	v_mfma_f32_16x16x32_bf16 v[118:121], v[162:165], v[178:181], v[118:121]
	v_mfma_f32_16x16x32_bf16 v[114:117], v[170:173], v[178:181], v[114:117]
	v_mfma_f32_16x16x32_bf16 v[102:105], v[162:165], v[186:189], v[102:105]
	v_mfma_f32_16x16x32_bf16 v[98:101], v[170:173], v[186:189], v[98:101]
	v_mfma_f32_16x16x32_bf16 v[86:89], v[162:165], v[208:211], v[86:89]
	v_mfma_f32_16x16x32_bf16 v[82:85], v[170:173], v[208:211], v[82:85]
	v_mfma_f32_16x16x32_bf16 v[70:73], v[162:165], v[216:219], v[70:73]
	v_mfma_f32_16x16x32_bf16 v[66:69], v[170:173], v[216:219], v[66:69]
	v_mfma_f32_16x16x32_bf16 v[118:121], v[166:169], v[182:185], v[118:121]
	v_mfma_f32_16x16x32_bf16 v[114:117], v[174:177], v[182:185], v[114:117]
	v_mfma_f32_16x16x32_bf16 v[102:105], v[166:169], v[204:207], v[102:105]
	v_mfma_f32_16x16x32_bf16 v[98:101], v[174:177], v[204:207], v[98:101]
	v_mfma_f32_16x16x32_bf16 v[86:89], v[166:169], v[212:215], v[86:89]
	v_mfma_f32_16x16x32_bf16 v[82:85], v[174:177], v[212:215], v[82:85]
	v_mfma_f32_16x16x32_bf16 v[70:73], v[166:169], v[230:233], v[70:73]
	v_mfma_f32_16x16x32_bf16 v[66:69], v[174:177], v[230:233], v[66:69]
	s_setprio 0
	s_barrier
	s_add_i32 s87, s87, s33
	v_lshl_add_u64 v[148:149], s[74:75], 0, v[190:191]
	s_mov_b32 m0, s87
	ds_read_b128 v[178:181], v153 offset:16384
	ds_read_b128 v[182:185], v153 offset:17408
	ds_read_b128 v[186:189], v153 offset:18432
	ds_read_b128 v[204:207], v153 offset:19456
	ds_read_b128 v[208:211], v153 offset:20480
	ds_read_b128 v[212:215], v153 offset:21504
	ds_read_b128 v[216:219], v153 offset:22528
	ds_read_b128 v[230:233], v153 offset:23552
	global_load_lds_dwordx4 v[148:149], off
	s_add_i32 m0, s87, 0x2000
	v_lshl_add_u64 v[220:221], s[74:75], 0, v[138:139]
	s_add_u32 s74, s74, s8
	s_addc_u32 s75, s75, s9
	s_add_i32 s87, s88, s33
	global_load_lds_dwordx4 v[220:221], off
	v_lshl_add_u64 v[234:235], s[74:75], 0, v[190:191]
	s_mov_b32 m0, s87
	v_lshl_add_u64 v[236:237], s[74:75], 0, v[138:139]
	global_load_lds_dwordx4 v[234:235], off
	s_add_i32 m0, s87, 0x2000
	v_lshl_add_u64 v[238:239], s[26:27], 0, v[134:135]
	global_load_lds_dwordx4 v[236:237], off
	s_mov_b32 m0, s34
	v_lshl_add_u64 v[240:241], s[26:27], 0, v[136:137]
	global_load_lds_dwordx4 v[238:239], off
	s_mov_b32 m0, s35
	s_nop 0
	global_load_lds_dwordx4 v[240:241], off
	s_waitcnt vmcnt(8)
	s_waitcnt lgkmcnt(0)
	s_barrier
	s_setprio 1
	s_waitcnt lgkmcnt(0)
	v_mfma_f32_16x16x32_bf16 v[62:65], v[130:133], v[178:181], v[62:65]
	v_mfma_f32_16x16x32_bf16 v[58:61], v[154:157], v[178:181], v[58:61]
	v_mfma_f32_16x16x32_bf16 v[46:49], v[130:133], v[186:189], v[46:49]
	v_mfma_f32_16x16x32_bf16 v[42:45], v[154:157], v[186:189], v[42:45]
	v_mfma_f32_16x16x32_bf16 v[30:33], v[130:133], v[208:211], v[30:33]
	v_mfma_f32_16x16x32_bf16 v[26:29], v[154:157], v[208:211], v[26:29]
	v_mfma_f32_16x16x32_bf16 v[14:17], v[130:133], v[216:219], v[14:17]
	v_mfma_f32_16x16x32_bf16 v[10:13], v[154:157], v[216:219], v[10:13]
	v_mfma_f32_16x16x32_bf16 v[62:65], v[144:147], v[182:185], v[62:65]
	v_mfma_f32_16x16x32_bf16 v[58:61], v[158:161], v[182:185], v[58:61]
	v_mfma_f32_16x16x32_bf16 v[46:49], v[144:147], v[204:207], v[46:49]
	v_mfma_f32_16x16x32_bf16 v[42:45], v[158:161], v[204:207], v[42:45]
	v_mfma_f32_16x16x32_bf16 v[30:33], v[144:147], v[212:215], v[30:33]
	v_mfma_f32_16x16x32_bf16 v[26:29], v[158:161], v[212:215], v[26:29]
	v_mfma_f32_16x16x32_bf16 v[14:17], v[144:147], v[230:233], v[14:17]
	v_mfma_f32_16x16x32_bf16 v[10:13], v[158:161], v[230:233], v[10:13]
	s_setprio 0
	s_setprio 1
	v_mfma_f32_16x16x32_bf16 v[54:57], v[162:165], v[178:181], v[54:57]
	v_mfma_f32_16x16x32_bf16 v[50:53], v[170:173], v[178:181], v[50:53]
	v_mfma_f32_16x16x32_bf16 v[38:41], v[162:165], v[186:189], v[38:41]
	v_mfma_f32_16x16x32_bf16 v[34:37], v[170:173], v[186:189], v[34:37]
	v_mfma_f32_16x16x32_bf16 v[22:25], v[162:165], v[208:211], v[22:25]
	v_mfma_f32_16x16x32_bf16 v[18:21], v[170:173], v[208:211], v[18:21]
	v_mfma_f32_16x16x32_bf16 v[6:9], v[162:165], v[216:219], v[6:9]
	v_mfma_f32_16x16x32_bf16 v[2:5], v[170:173], v[216:219], v[2:5]
	v_mfma_f32_16x16x32_bf16 v[54:57], v[166:169], v[182:185], v[54:57]
	v_mfma_f32_16x16x32_bf16 v[50:53], v[174:177], v[182:185], v[50:53]
	v_mfma_f32_16x16x32_bf16 v[38:41], v[166:169], v[204:207], v[38:41]
	v_mfma_f32_16x16x32_bf16 v[34:37], v[174:177], v[204:207], v[34:37]
	v_mfma_f32_16x16x32_bf16 v[22:25], v[166:169], v[212:215], v[22:25]
	v_mfma_f32_16x16x32_bf16 v[18:21], v[174:177], v[212:215], v[18:21]
	v_mfma_f32_16x16x32_bf16 v[6:9], v[166:169], v[230:233], v[6:9]
	v_mfma_f32_16x16x32_bf16 v[2:5], v[174:177], v[230:233], v[2:5]
	s_setprio 0
	s_barrier
	s_add_i32 s74, 0, 0x18000
	s_add_i32 s75, 0, 0x1c000
	v_add_u32_e32 v158, s74, v152
	v_add_u32_e32 v174, s75, v152
	ds_read_b128 v[130:133], v158
	ds_read_b128 v[144:147], v158 offset:1024
	ds_read_b128 v[154:157], v158 offset:2048
	ds_read_b128 v[158:161], v158 offset:3072
	ds_read_b128 v[162:165], v174
	ds_read_b128 v[166:169], v174 offset:1024
	ds_read_b128 v[170:173], v174 offset:2048
	ds_read_b128 v[174:177], v174 offset:3072
	s_add_u32 s26, s26, s8
	s_addc_u32 s27, s27, s9
	s_mov_b32 m0, s36
	v_lshl_add_u64 v[242:243], s[26:27], 0, v[134:135]
	ds_read_b128 v[178:181], v153 offset:32768
	ds_read_b128 v[182:185], v153 offset:33792
	ds_read_b128 v[186:189], v153 offset:34816
	ds_read_b128 v[204:207], v153 offset:35840
	ds_read_b128 v[208:211], v153 offset:36864
	ds_read_b128 v[212:215], v153 offset:37888
	ds_read_b128 v[216:219], v153 offset:38912
	ds_read_b128 v[230:233], v153 offset:39936
	global_load_lds_dwordx4 v[242:243], off
	v_lshl_add_u64 v[242:243], s[26:27], 0, v[136:137]
	s_mov_b32 m0, s37
	s_nop 0
	global_load_lds_dwordx4 v[242:243], off
	s_waitcnt vmcnt(8)
	s_waitcnt lgkmcnt(0)
	s_barrier
	s_setprio 1
	s_waitcnt lgkmcnt(0)
	v_mfma_f32_16x16x32_bf16 v[126:129], v[130:133], v[178:181], v[126:129]
	v_mfma_f32_16x16x32_bf16 v[122:125], v[154:157], v[178:181], v[122:125]
	v_mfma_f32_16x16x32_bf16 v[110:113], v[130:133], v[186:189], v[110:113]
	v_mfma_f32_16x16x32_bf16 v[106:109], v[154:157], v[186:189], v[106:109]
	v_mfma_f32_16x16x32_bf16 v[94:97], v[130:133], v[208:211], v[94:97]
	v_mfma_f32_16x16x32_bf16 v[90:93], v[154:157], v[208:211], v[90:93]
	v_mfma_f32_16x16x32_bf16 v[78:81], v[130:133], v[216:219], v[78:81]
	v_mfma_f32_16x16x32_bf16 v[74:77], v[154:157], v[216:219], v[74:77]
	v_mfma_f32_16x16x32_bf16 v[126:129], v[144:147], v[182:185], v[126:129]
	v_mfma_f32_16x16x32_bf16 v[122:125], v[158:161], v[182:185], v[122:125]
	v_mfma_f32_16x16x32_bf16 v[110:113], v[144:147], v[204:207], v[110:113]
	v_mfma_f32_16x16x32_bf16 v[106:109], v[158:161], v[204:207], v[106:109]
	v_mfma_f32_16x16x32_bf16 v[94:97], v[144:147], v[212:215], v[94:97]
	v_mfma_f32_16x16x32_bf16 v[90:93], v[158:161], v[212:215], v[90:93]
	v_mfma_f32_16x16x32_bf16 v[78:81], v[144:147], v[230:233], v[78:81]
	v_mfma_f32_16x16x32_bf16 v[74:77], v[158:161], v[230:233], v[74:77]
	s_setprio 0
	s_setprio 1
	v_mfma_f32_16x16x32_bf16 v[118:121], v[162:165], v[178:181], v[118:121]
	v_mfma_f32_16x16x32_bf16 v[114:117], v[170:173], v[178:181], v[114:117]
	v_mfma_f32_16x16x32_bf16 v[102:105], v[162:165], v[186:189], v[102:105]
	v_mfma_f32_16x16x32_bf16 v[98:101], v[170:173], v[186:189], v[98:101]
	v_mfma_f32_16x16x32_bf16 v[86:89], v[162:165], v[208:211], v[86:89]
	v_mfma_f32_16x16x32_bf16 v[82:85], v[170:173], v[208:211], v[82:85]
	v_mfma_f32_16x16x32_bf16 v[70:73], v[162:165], v[216:219], v[70:73]
	v_mfma_f32_16x16x32_bf16 v[66:69], v[170:173], v[216:219], v[66:69]
	v_mfma_f32_16x16x32_bf16 v[118:121], v[166:169], v[182:185], v[118:121]
	v_mfma_f32_16x16x32_bf16 v[114:117], v[174:177], v[182:185], v[114:117]
	v_mfma_f32_16x16x32_bf16 v[102:105], v[166:169], v[204:207], v[102:105]
	v_mfma_f32_16x16x32_bf16 v[98:101], v[174:177], v[204:207], v[98:101]
	v_mfma_f32_16x16x32_bf16 v[86:89], v[166:169], v[212:215], v[86:89]
	v_mfma_f32_16x16x32_bf16 v[82:85], v[174:177], v[212:215], v[82:85]
	v_mfma_f32_16x16x32_bf16 v[70:73], v[166:169], v[230:233], v[70:73]
	v_mfma_f32_16x16x32_bf16 v[66:69], v[174:177], v[230:233], v[66:69]
	s_setprio 0
	s_barrier
	s_add_i32 s26, s74, s33
	v_lshl_add_u64 v[148:149], v[148:149], 0, s[68:69]
	s_mov_b32 m0, s26
	ds_read_b128 v[178:181], v153 offset:49152
	ds_read_b128 v[182:185], v153 offset:50176
	ds_read_b128 v[186:189], v153 offset:51200
	ds_read_b128 v[204:207], v153 offset:52224
	ds_read_b128 v[208:211], v153 offset:53248
	ds_read_b128 v[212:215], v153 offset:54272
	ds_read_b128 v[216:219], v153 offset:55296
	ds_read_b128 v[230:233], v153 offset:56320
	global_load_lds_dwordx4 v[148:149], off
	v_lshl_add_u64 v[148:149], v[220:221], 0, s[68:69]
	s_add_i32 m0, s26, 0x2000
	s_add_i32 s26, s75, s33
	global_load_lds_dwordx4 v[148:149], off
	v_lshl_add_u64 v[148:149], v[234:235], 0, s[68:69]
	s_mov_b32 m0, s26
	s_nop 0
	global_load_lds_dwordx4 v[148:149], off
	v_lshl_add_u64 v[148:149], v[236:237], 0, s[68:69]
	s_add_i32 m0, s26, 0x2000
	s_nop 0
	global_load_lds_dwordx4 v[148:149], off
	v_lshl_add_u64 v[148:149], v[238:239], 0, s[68:69]
	s_mov_b32 m0, s72
	s_nop 0
	global_load_lds_dwordx4 v[148:149], off
	v_lshl_add_u64 v[148:149], v[240:241], 0, s[68:69]
	s_mov_b32 m0, s78
	s_nop 0
	global_load_lds_dwordx4 v[148:149], off
	s_waitcnt vmcnt(8)
	s_waitcnt lgkmcnt(0)
	s_barrier
	s_setprio 1
	s_waitcnt lgkmcnt(0)
	v_mfma_f32_16x16x32_bf16 v[62:65], v[130:133], v[178:181], v[62:65]
	v_mfma_f32_16x16x32_bf16 v[58:61], v[154:157], v[178:181], v[58:61]
	v_mfma_f32_16x16x32_bf16 v[46:49], v[130:133], v[186:189], v[46:49]
	v_mfma_f32_16x16x32_bf16 v[42:45], v[154:157], v[186:189], v[42:45]
	v_mfma_f32_16x16x32_bf16 v[30:33], v[130:133], v[208:211], v[30:33]
	v_mfma_f32_16x16x32_bf16 v[26:29], v[154:157], v[208:211], v[26:29]
	v_mfma_f32_16x16x32_bf16 v[14:17], v[130:133], v[216:219], v[14:17]
	v_mfma_f32_16x16x32_bf16 v[10:13], v[154:157], v[216:219], v[10:13]
	v_mfma_f32_16x16x32_bf16 v[62:65], v[144:147], v[182:185], v[62:65]
	v_mfma_f32_16x16x32_bf16 v[58:61], v[158:161], v[182:185], v[58:61]
	v_mfma_f32_16x16x32_bf16 v[46:49], v[144:147], v[204:207], v[46:49]
	v_mfma_f32_16x16x32_bf16 v[42:45], v[158:161], v[204:207], v[42:45]
	v_mfma_f32_16x16x32_bf16 v[30:33], v[144:147], v[212:215], v[30:33]
	v_mfma_f32_16x16x32_bf16 v[26:29], v[158:161], v[212:215], v[26:29]
	v_mfma_f32_16x16x32_bf16 v[14:17], v[144:147], v[230:233], v[14:17]
	v_mfma_f32_16x16x32_bf16 v[10:13], v[158:161], v[230:233], v[10:13]
	s_setprio 0
	s_setprio 1
	v_mfma_f32_16x16x32_bf16 v[54:57], v[162:165], v[178:181], v[54:57]
	v_mfma_f32_16x16x32_bf16 v[50:53], v[170:173], v[178:181], v[50:53]
	v_mfma_f32_16x16x32_bf16 v[38:41], v[162:165], v[186:189], v[38:41]
	v_mfma_f32_16x16x32_bf16 v[34:37], v[170:173], v[186:189], v[34:37]
	v_mfma_f32_16x16x32_bf16 v[22:25], v[162:165], v[208:211], v[22:25]
	v_mfma_f32_16x16x32_bf16 v[18:21], v[170:173], v[208:211], v[18:21]
	v_mfma_f32_16x16x32_bf16 v[6:9], v[162:165], v[216:219], v[6:9]
	v_mfma_f32_16x16x32_bf16 v[2:5], v[170:173], v[216:219], v[2:5]
	v_mfma_f32_16x16x32_bf16 v[54:57], v[166:169], v[182:185], v[54:57]
	v_mfma_f32_16x16x32_bf16 v[50:53], v[174:177], v[182:185], v[50:53]
	v_mfma_f32_16x16x32_bf16 v[38:41], v[166:169], v[204:207], v[38:41]
	v_mfma_f32_16x16x32_bf16 v[34:37], v[174:177], v[204:207], v[34:37]
	v_mfma_f32_16x16x32_bf16 v[22:25], v[166:169], v[212:215], v[22:25]
	v_mfma_f32_16x16x32_bf16 v[18:21], v[174:177], v[212:215], v[18:21]
	v_mfma_f32_16x16x32_bf16 v[6:9], v[166:169], v[230:233], v[6:9]
	v_mfma_f32_16x16x32_bf16 v[2:5], v[174:177], v[230:233], v[2:5]
	s_setprio 0
	s_add_u32 s24, s24, 0x100
	s_addc_u32 s25, s25, 0
	s_add_u32 s28, s28, 0x100
	s_addc_u32 s29, s29, 0
	s_cmp_ge_i32 s86, s85
	s_mov_b32 s26, s86
	s_barrier
	s_cbranch_scc0 .LBB0_590
	s_and_b64 vcc, exec, s[16:17]
	s_cbranch_vccz .LBB0_593
	s_barrier

.LBB0_1658:
	s_add_u32 s10, s34, s44
	s_addc_u32 s11, s35, s45
	s_add_u32 s10, s10, 0x100
	s_addc_u32 s11, s11, 0
	s_add_u32 s72, s33, s44
	s_addc_u32 s74, s48, s45
	s_add_i32 s75, 0, 0x10000
	s_cmpk_eq_i32 s44, 0x700
	s_cselect_b32 s11, s29, s11
	s_cselect_b32 s10, s28, s10
	s_cselect_b32 s81, s31, s74
	s_cselect_b32 s80, s30, s72
	s_add_i32 s72, 0, 0x14000
	v_add_u32_e32 v146, s75, v184
	v_add_u32_e32 v158, s72, v184
	ds_read_b128 v[134:137], v146
	ds_read_b128 v[138:141], v146 offset:1024
	ds_read_b128 v[142:145], v146 offset:2048
	ds_read_b128 v[146:149], v146 offset:3072
	ds_read_b128 v[150:153], v158
	ds_read_b128 v[154:157], v158 offset:1024
	ds_read_b128 v[178:181], v158 offset:2048
	ds_read_b128 v[186:189], v158 offset:3072
	v_lshl_add_u64 v[158:159], v[130:131], 0, s[44:45]
	s_add_i32 m0, s14, 0xc000
	ds_read_b128 v[204:207], v185
	ds_read_b128 v[208:211], v185 offset:1024
	ds_read_b128 v[212:215], v185 offset:2048
	ds_read_b128 v[216:219], v185 offset:3072
	ds_read_b128 v[226:229], v185 offset:4096
	ds_read_b128 v[230:233], v185 offset:5120
	ds_read_b128 v[234:237], v185 offset:6144
	ds_read_b128 v[238:241], v185 offset:7168
	global_load_lds_dwordx4 v[158:159], off
	v_lshl_add_u64 v[158:159], v[132:133], 0, s[44:45]
	s_add_i32 m0, s14, 0xe000
	s_nop 0
	global_load_lds_dwordx4 v[158:159], off
	s_waitcnt vmcnt(8)
	s_waitcnt lgkmcnt(0)
	s_barrier
	s_setprio 1
	s_waitcnt lgkmcnt(0)
	v_mfma_f32_16x16x32_bf16 v[126:129], v[134:137], v[204:207], v[126:129]
	v_mfma_f32_16x16x32_bf16 v[122:125], v[142:145], v[204:207], v[122:125]
	v_mfma_f32_16x16x32_bf16 v[110:113], v[134:137], v[212:215], v[110:113]
	v_mfma_f32_16x16x32_bf16 v[106:109], v[142:145], v[212:215], v[106:109]
	v_mfma_f32_16x16x32_bf16 v[94:97], v[134:137], v[226:229], v[94:97]
	v_mfma_f32_16x16x32_bf16 v[90:93], v[142:145], v[226:229], v[90:93]
	v_mfma_f32_16x16x32_bf16 v[78:81], v[134:137], v[234:237], v[78:81]
	v_mfma_f32_16x16x32_bf16 v[74:77], v[142:145], v[234:237], v[74:77]
	v_mfma_f32_16x16x32_bf16 v[126:129], v[138:141], v[208:211], v[126:129]
	v_mfma_f32_16x16x32_bf16 v[122:125], v[146:149], v[208:211], v[122:125]
	v_mfma_f32_16x16x32_bf16 v[110:113], v[138:141], v[216:219], v[110:113]
	v_mfma_f32_16x16x32_bf16 v[106:109], v[146:149], v[216:219], v[106:109]
	v_mfma_f32_16x16x32_bf16 v[94:97], v[138:141], v[230:233], v[94:97]
	v_mfma_f32_16x16x32_bf16 v[90:93], v[146:149], v[230:233], v[90:93]
	v_mfma_f32_16x16x32_bf16 v[78:81], v[138:141], v[238:241], v[78:81]
	v_mfma_f32_16x16x32_bf16 v[74:77], v[146:149], v[238:241], v[74:77]
	s_setprio 0
	s_setprio 1
	v_mfma_f32_16x16x32_bf16 v[118:121], v[150:153], v[204:207], v[118:121]
	v_mfma_f32_16x16x32_bf16 v[114:117], v[178:181], v[204:207], v[114:117]
	v_mfma_f32_16x16x32_bf16 v[102:105], v[150:153], v[212:215], v[102:105]
	v_mfma_f32_16x16x32_bf16 v[98:101], v[178:181], v[212:215], v[98:101]
	v_mfma_f32_16x16x32_bf16 v[86:89], v[150:153], v[226:229], v[86:89]
	v_mfma_f32_16x16x32_bf16 v[82:85], v[178:181], v[226:229], v[82:85]
	v_mfma_f32_16x16x32_bf16 v[70:73], v[150:153], v[234:237], v[70:73]
	v_mfma_f32_16x16x32_bf16 v[66:69], v[178:181], v[234:237], v[66:69]
	v_mfma_f32_16x16x32_bf16 v[118:121], v[154:157], v[208:211], v[118:121]
	v_mfma_f32_16x16x32_bf16 v[114:117], v[186:189], v[208:211], v[114:117]
	v_mfma_f32_16x16x32_bf16 v[102:105], v[154:157], v[216:219], v[102:105]
	v_mfma_f32_16x16x32_bf16 v[98:101], v[186:189], v[216:219], v[98:101]
	v_mfma_f32_16x16x32_bf16 v[86:89], v[154:157], v[230:233], v[86:89]
	v_mfma_f32_16x16x32_bf16 v[82:85], v[186:189], v[230:233], v[82:85]
	v_mfma_f32_16x16x32_bf16 v[70:73], v[154:157], v[238:241], v[70:73]
	v_mfma_f32_16x16x32_bf16 v[66:69], v[186:189], v[238:241], v[66:69]
	s_setprio 0
	s_barrier
	s_add_i32 s74, s75, s82
	v_lshl_add_u64 v[158:159], s[80:81], 0, v[162:163]
	s_mov_b32 m0, s74
	ds_read_b128 v[204:207], v185 offset:16384
	ds_read_b128 v[208:211], v185 offset:17408
	ds_read_b128 v[212:215], v185 offset:18432
	ds_read_b128 v[216:219], v185 offset:19456
	ds_read_b128 v[226:229], v185 offset:20480
	ds_read_b128 v[230:233], v185 offset:21504
	ds_read_b128 v[234:237], v185 offset:22528
	ds_read_b128 v[238:241], v185 offset:23552
	global_load_lds_dwordx4 v[158:159], off
	s_add_i32 m0, s74, 0x2000
	v_lshl_add_u64 v[182:183], s[80:81], 0, v[166:167]
	s_add_u32 s80, s80, s4
	s_addc_u32 s81, s81, s5
	s_add_i32 s72, s72, s82
	global_load_lds_dwordx4 v[182:183], off
	v_lshl_add_u64 v[220:221], s[80:81], 0, v[162:163]
	s_mov_b32 m0, s72
	v_lshl_add_u64 v[242:243], s[80:81], 0, v[166:167]
	global_load_lds_dwordx4 v[220:221], off
	s_add_i32 m0, s72, 0x2000
	v_lshl_add_u64 v[244:245], s[10:11], 0, v[160:161]
	global_load_lds_dwordx4 v[242:243], off
	s_mov_b32 m0, s14
	v_lshl_add_u64 v[246:247], s[10:11], 0, v[164:165]
	global_load_lds_dwordx4 v[244:245], off
	s_mov_b32 m0, s15
	s_nop 0
	global_load_lds_dwordx4 v[246:247], off
	s_waitcnt vmcnt(8)
	s_waitcnt lgkmcnt(0)
	s_barrier
	s_setprio 1
	s_waitcnt lgkmcnt(0)
	v_mfma_f32_16x16x32_bf16 v[62:65], v[134:137], v[204:207], v[62:65]
	v_mfma_f32_16x16x32_bf16 v[58:61], v[142:145], v[204:207], v[58:61]
	v_mfma_f32_16x16x32_bf16 v[46:49], v[134:137], v[212:215], v[46:49]
	v_mfma_f32_16x16x32_bf16 v[42:45], v[142:145], v[212:215], v[42:45]
	v_mfma_f32_16x16x32_bf16 v[30:33], v[134:137], v[226:229], v[30:33]
	v_mfma_f32_16x16x32_bf16 v[26:29], v[142:145], v[226:229], v[26:29]
	v_mfma_f32_16x16x32_bf16 v[14:17], v[134:137], v[234:237], v[14:17]
	v_mfma_f32_16x16x32_bf16 v[10:13], v[142:145], v[234:237], v[10:13]
	v_mfma_f32_16x16x32_bf16 v[62:65], v[138:141], v[208:211], v[62:65]
	v_mfma_f32_16x16x32_bf16 v[58:61], v[146:149], v[208:211], v[58:61]
	v_mfma_f32_16x16x32_bf16 v[46:49], v[138:141], v[216:219], v[46:49]
	v_mfma_f32_16x16x32_bf16 v[42:45], v[146:149], v[216:219], v[42:45]
	v_mfma_f32_16x16x32_bf16 v[30:33], v[138:141], v[230:233], v[30:33]
	v_mfma_f32_16x16x32_bf16 v[26:29], v[146:149], v[230:233], v[26:29]
	v_mfma_f32_16x16x32_bf16 v[14:17], v[138:141], v[238:241], v[14:17]
	v_mfma_f32_16x16x32_bf16 v[10:13], v[146:149], v[238:241], v[10:13]
	s_setprio 0
	s_setprio 1
	v_mfma_f32_16x16x32_bf16 v[54:57], v[150:153], v[204:207], v[54:57]
	v_mfma_f32_16x16x32_bf16 v[50:53], v[178:181], v[204:207], v[50:53]
	v_mfma_f32_16x16x32_bf16 v[38:41], v[150:153], v[212:215], v[38:41]
	v_mfma_f32_16x16x32_bf16 v[34:37], v[178:181], v[212:215], v[34:37]
	v_mfma_f32_16x16x32_bf16 v[22:25], v[150:153], v[226:229], v[22:25]
	v_mfma_f32_16x16x32_bf16 v[18:21], v[178:181], v[226:229], v[18:21]
	v_mfma_f32_16x16x32_bf16 v[6:9], v[150:153], v[234:237], v[6:9]
	v_mfma_f32_16x16x32_bf16 v[2:5], v[178:181], v[234:237], v[2:5]
	v_mfma_f32_16x16x32_bf16 v[54:57], v[154:157], v[208:211], v[54:57]
	v_mfma_f32_16x16x32_bf16 v[50:53], v[186:189], v[208:211], v[50:53]
	v_mfma_f32_16x16x32_bf16 v[38:41], v[154:157], v[216:219], v[38:41]
	v_mfma_f32_16x16x32_bf16 v[34:37], v[186:189], v[216:219], v[34:37]
	v_mfma_f32_16x16x32_bf16 v[22:25], v[154:157], v[230:233], v[22:25]
	v_mfma_f32_16x16x32_bf16 v[18:21], v[186:189], v[230:233], v[18:21]
	v_mfma_f32_16x16x32_bf16 v[6:9], v[154:157], v[238:241], v[6:9]
	v_mfma_f32_16x16x32_bf16 v[2:5], v[186:189], v[238:241], v[2:5]
	s_setprio 0
	s_barrier
	s_add_i32 s72, 0, 0x18000
	s_add_i32 s74, 0, 0x1c000
	v_add_u32_e32 v146, s72, v184
	v_add_u32_e32 v186, s74, v184
	ds_read_b128 v[134:137], v146
	ds_read_b128 v[138:141], v146 offset:1024
	ds_read_b128 v[142:145], v146 offset:2048
	ds_read_b128 v[146:149], v146 offset:3072
	ds_read_b128 v[150:153], v186
	ds_read_b128 v[154:157], v186 offset:1024
	ds_read_b128 v[178:181], v186 offset:2048
	ds_read_b128 v[186:189], v186 offset:3072
	s_add_u32 s10, s10, s4
	s_addc_u32 s11, s11, s5
	s_mov_b32 m0, s16
	v_lshl_add_u64 v[248:249], s[10:11], 0, v[160:161]
	ds_read_b128 v[204:207], v185 offset:32768
	ds_read_b128 v[208:211], v185 offset:33792
	ds_read_b128 v[212:215], v185 offset:34816
	ds_read_b128 v[216:219], v185 offset:35840
	ds_read_b128 v[226:229], v185 offset:36864
	ds_read_b128 v[230:233], v185 offset:37888
	ds_read_b128 v[234:237], v185 offset:38912
	ds_read_b128 v[238:241], v185 offset:39936
	global_load_lds_dwordx4 v[248:249], off
	v_lshl_add_u64 v[248:249], s[10:11], 0, v[164:165]
	s_mov_b32 m0, s17
	s_nop 0
	global_load_lds_dwordx4 v[248:249], off
	s_waitcnt vmcnt(8)
	s_waitcnt lgkmcnt(0)
	s_barrier
	s_setprio 1
	s_waitcnt lgkmcnt(0)
	v_mfma_f32_16x16x32_bf16 v[126:129], v[134:137], v[204:207], v[126:129]
	v_mfma_f32_16x16x32_bf16 v[122:125], v[142:145], v[204:207], v[122:125]
	v_mfma_f32_16x16x32_bf16 v[110:113], v[134:137], v[212:215], v[110:113]
	v_mfma_f32_16x16x32_bf16 v[106:109], v[142:145], v[212:215], v[106:109]
	v_mfma_f32_16x16x32_bf16 v[94:97], v[134:137], v[226:229], v[94:97]
	v_mfma_f32_16x16x32_bf16 v[90:93], v[142:145], v[226:229], v[90:93]
	v_mfma_f32_16x16x32_bf16 v[78:81], v[134:137], v[234:237], v[78:81]
	v_mfma_f32_16x16x32_bf16 v[74:77], v[142:145], v[234:237], v[74:77]
	v_mfma_f32_16x16x32_bf16 v[126:129], v[138:141], v[208:211], v[126:129]
	v_mfma_f32_16x16x32_bf16 v[122:125], v[146:149], v[208:211], v[122:125]
	v_mfma_f32_16x16x32_bf16 v[110:113], v[138:141], v[216:219], v[110:113]
	v_mfma_f32_16x16x32_bf16 v[106:109], v[146:149], v[216:219], v[106:109]
	v_mfma_f32_16x16x32_bf16 v[94:97], v[138:141], v[230:233], v[94:97]
	v_mfma_f32_16x16x32_bf16 v[90:93], v[146:149], v[230:233], v[90:93]
	v_mfma_f32_16x16x32_bf16 v[78:81], v[138:141], v[238:241], v[78:81]
	v_mfma_f32_16x16x32_bf16 v[74:77], v[146:149], v[238:241], v[74:77]
	s_setprio 0
	s_setprio 1
	v_mfma_f32_16x16x32_bf16 v[118:121], v[150:153], v[204:207], v[118:121]
	v_mfma_f32_16x16x32_bf16 v[114:117], v[178:181], v[204:207], v[114:117]
	v_mfma_f32_16x16x32_bf16 v[102:105], v[150:153], v[212:215], v[102:105]
	v_mfma_f32_16x16x32_bf16 v[98:101], v[178:181], v[212:215], v[98:101]
	v_mfma_f32_16x16x32_bf16 v[86:89], v[150:153], v[226:229], v[86:89]
	v_mfma_f32_16x16x32_bf16 v[82:85], v[178:181], v[226:229], v[82:85]
	v_mfma_f32_16x16x32_bf16 v[70:73], v[150:153], v[234:237], v[70:73]
	v_mfma_f32_16x16x32_bf16 v[66:69], v[178:181], v[234:237], v[66:69]
	v_mfma_f32_16x16x32_bf16 v[118:121], v[154:157], v[208:211], v[118:121]
	v_mfma_f32_16x16x32_bf16 v[114:117], v[186:189], v[208:211], v[114:117]
	v_mfma_f32_16x16x32_bf16 v[102:105], v[154:157], v[216:219], v[102:105]
	v_mfma_f32_16x16x32_bf16 v[98:101], v[186:189], v[216:219], v[98:101]
	v_mfma_f32_16x16x32_bf16 v[86:89], v[154:157], v[230:233], v[86:89]
	v_mfma_f32_16x16x32_bf16 v[82:85], v[186:189], v[230:233], v[82:85]
	v_mfma_f32_16x16x32_bf16 v[70:73], v[154:157], v[238:241], v[70:73]
	v_mfma_f32_16x16x32_bf16 v[66:69], v[186:189], v[238:241], v[66:69]
	s_setprio 0
	s_barrier
	s_add_i32 s10, s72, s82
	v_lshl_add_u64 v[158:159], v[158:159], 0, s[68:69]
	s_mov_b32 m0, s10
	ds_read_b128 v[204:207], v185 offset:49152
	ds_read_b128 v[208:211], v185 offset:50176
	ds_read_b128 v[212:215], v185 offset:51200
	ds_read_b128 v[216:219], v185 offset:52224
	ds_read_b128 v[226:229], v185 offset:53248
	ds_read_b128 v[230:233], v185 offset:54272
	ds_read_b128 v[234:237], v185 offset:55296
	ds_read_b128 v[238:241], v185 offset:56320
	global_load_lds_dwordx4 v[158:159], off
	v_lshl_add_u64 v[158:159], v[182:183], 0, s[68:69]
	s_add_i32 m0, s10, 0x2000
	s_add_i32 s10, s74, s82
	global_load_lds_dwordx4 v[158:159], off
	v_lshl_add_u64 v[158:159], v[220:221], 0, s[68:69]
	s_mov_b32 m0, s10
	s_nop 0
	global_load_lds_dwordx4 v[158:159], off
	v_lshl_add_u64 v[158:159], v[242:243], 0, s[68:69]
	s_add_i32 m0, s10, 0x2000
	s_nop 0
	global_load_lds_dwordx4 v[158:159], off
	v_lshl_add_u64 v[158:159], v[244:245], 0, s[68:69]
	s_mov_b32 m0, s79
	s_nop 0
	global_load_lds_dwordx4 v[158:159], off
	v_lshl_add_u64 v[158:159], v[246:247], 0, s[68:69]
	s_mov_b32 m0, s78
	s_nop 0
	global_load_lds_dwordx4 v[158:159], off
	s_waitcnt vmcnt(8)
	s_waitcnt lgkmcnt(0)
	s_barrier
	s_setprio 1
	s_waitcnt lgkmcnt(0)
	v_mfma_f32_16x16x32_bf16 v[62:65], v[134:137], v[204:207], v[62:65]
	v_mfma_f32_16x16x32_bf16 v[58:61], v[142:145], v[204:207], v[58:61]
	v_mfma_f32_16x16x32_bf16 v[46:49], v[134:137], v[212:215], v[46:49]
	v_mfma_f32_16x16x32_bf16 v[42:45], v[142:145], v[212:215], v[42:45]
	v_mfma_f32_16x16x32_bf16 v[30:33], v[134:137], v[226:229], v[30:33]
	v_mfma_f32_16x16x32_bf16 v[26:29], v[142:145], v[226:229], v[26:29]
	v_mfma_f32_16x16x32_bf16 v[14:17], v[134:137], v[234:237], v[14:17]
	v_mfma_f32_16x16x32_bf16 v[10:13], v[142:145], v[234:237], v[10:13]
	v_mfma_f32_16x16x32_bf16 v[62:65], v[138:141], v[208:211], v[62:65]
	v_mfma_f32_16x16x32_bf16 v[58:61], v[146:149], v[208:211], v[58:61]
	v_mfma_f32_16x16x32_bf16 v[46:49], v[138:141], v[216:219], v[46:49]
	v_mfma_f32_16x16x32_bf16 v[42:45], v[146:149], v[216:219], v[42:45]
	v_mfma_f32_16x16x32_bf16 v[30:33], v[138:141], v[230:233], v[30:33]
	v_mfma_f32_16x16x32_bf16 v[26:29], v[146:149], v[230:233], v[26:29]
	v_mfma_f32_16x16x32_bf16 v[14:17], v[138:141], v[238:241], v[14:17]
	v_mfma_f32_16x16x32_bf16 v[10:13], v[146:149], v[238:241], v[10:13]
	s_setprio 0
	s_setprio 1
	v_mfma_f32_16x16x32_bf16 v[54:57], v[150:153], v[204:207], v[54:57]
	v_mfma_f32_16x16x32_bf16 v[50:53], v[178:181], v[204:207], v[50:53]
	v_mfma_f32_16x16x32_bf16 v[38:41], v[150:153], v[212:215], v[38:41]
	v_mfma_f32_16x16x32_bf16 v[34:37], v[178:181], v[212:215], v[34:37]
	v_mfma_f32_16x16x32_bf16 v[22:25], v[150:153], v[226:229], v[22:25]
	v_mfma_f32_16x16x32_bf16 v[18:21], v[178:181], v[226:229], v[18:21]
	v_mfma_f32_16x16x32_bf16 v[6:9], v[150:153], v[234:237], v[6:9]
	v_mfma_f32_16x16x32_bf16 v[2:5], v[178:181], v[234:237], v[2:5]
	v_mfma_f32_16x16x32_bf16 v[54:57], v[154:157], v[208:211], v[54:57]
	v_mfma_f32_16x16x32_bf16 v[50:53], v[186:189], v[208:211], v[50:53]
	v_mfma_f32_16x16x32_bf16 v[38:41], v[154:157], v[216:219], v[38:41]
	v_mfma_f32_16x16x32_bf16 v[34:37], v[186:189], v[216:219], v[34:37]
	v_mfma_f32_16x16x32_bf16 v[22:25], v[154:157], v[230:233], v[22:25]
	v_mfma_f32_16x16x32_bf16 v[18:21], v[186:189], v[230:233], v[18:21]
	v_mfma_f32_16x16x32_bf16 v[6:9], v[154:157], v[238:241], v[6:9]
	v_mfma_f32_16x16x32_bf16 v[2:5], v[186:189], v[238:241], v[2:5]
	s_setprio 0
	s_add_i32 s49, s49, 2
	s_add_u32 s44, s44, 0x100
	s_addc_u32 s45, s45, 0
	s_cmp_gt_u32 s49, 13
	s_barrier
	s_cbranch_scc0 .LBB0_1658
	s_and_b64 vcc, exec, s[24:25]
	s_cbranch_vccz .LBB0_1661
	s_barrier

.LBB0_1766:
	s_add_i32 s82, s26, 2
	s_add_u32 s74, s24, 0x80
	s_addc_u32 s27, s25, 0
	s_add_i32 s85, 0, 0x10000
	s_cmp_eq_u32 s19, s26
	s_cselect_b32 s27, s21, s27
	s_cselect_b32 s26, s20, s74
	v_add_u32_e32 v148, s85, v152
	s_cselect_b32 s75, s23, s29
	s_cselect_b32 s74, s22, s28
	s_add_i32 s86, 0, 0x14000
	ds_read_b128 v[130:133], v148
	ds_read_b128 v[144:147], v148 offset:1024
	ds_read_b128 v[154:157], v148 offset:2048
	ds_read_b128 v[158:161], v148 offset:3072
	v_add_u32_e32 v148, s86, v152
	ds_read_b128 v[162:165], v148
	ds_read_b128 v[166:169], v148 offset:1024
	ds_read_b128 v[170:173], v148 offset:2048
	ds_read_b128 v[174:177], v148 offset:3072
	v_lshl_add_u64 v[148:149], s[24:25], 0, v[140:141]
	s_add_i32 m0, s34, 0xc000
	ds_read_b128 v[178:181], v153
	ds_read_b128 v[182:185], v153 offset:1024
	ds_read_b128 v[186:189], v153 offset:2048
	ds_read_b128 v[204:207], v153 offset:3072
	ds_read_b128 v[208:211], v153 offset:4096
	ds_read_b128 v[212:215], v153 offset:5120
	ds_read_b128 v[216:219], v153 offset:6144
	ds_read_b128 v[226:229], v153 offset:7168
	global_load_lds_dwordx4 v[148:149], off
	v_lshl_add_u64 v[148:149], s[24:25], 0, v[142:143]
	s_add_i32 m0, s34, 0xe000
	s_nop 0
	global_load_lds_dwordx4 v[148:149], off
	s_waitcnt vmcnt(8)
	s_waitcnt lgkmcnt(0)
	s_barrier
	s_setprio 1
	s_waitcnt lgkmcnt(0)
	v_mfma_f32_16x16x32_bf16 v[126:129], v[130:133], v[178:181], v[126:129]
	v_mfma_f32_16x16x32_bf16 v[122:125], v[154:157], v[178:181], v[122:125]
	v_mfma_f32_16x16x32_bf16 v[110:113], v[130:133], v[186:189], v[110:113]
	v_mfma_f32_16x16x32_bf16 v[106:109], v[154:157], v[186:189], v[106:109]
	v_mfma_f32_16x16x32_bf16 v[94:97], v[130:133], v[208:211], v[94:97]
	v_mfma_f32_16x16x32_bf16 v[90:93], v[154:157], v[208:211], v[90:93]
	v_mfma_f32_16x16x32_bf16 v[78:81], v[130:133], v[216:219], v[78:81]
	v_mfma_f32_16x16x32_bf16 v[74:77], v[154:157], v[216:219], v[74:77]
	v_mfma_f32_16x16x32_bf16 v[126:129], v[144:147], v[182:185], v[126:129]
	v_mfma_f32_16x16x32_bf16 v[122:125], v[158:161], v[182:185], v[122:125]
	v_mfma_f32_16x16x32_bf16 v[110:113], v[144:147], v[204:207], v[110:113]
	v_mfma_f32_16x16x32_bf16 v[106:109], v[158:161], v[204:207], v[106:109]
	v_mfma_f32_16x16x32_bf16 v[94:97], v[144:147], v[212:215], v[94:97]
	v_mfma_f32_16x16x32_bf16 v[90:93], v[158:161], v[212:215], v[90:93]
	v_mfma_f32_16x16x32_bf16 v[78:81], v[144:147], v[226:229], v[78:81]
	v_mfma_f32_16x16x32_bf16 v[74:77], v[158:161], v[226:229], v[74:77]
	s_setprio 0
	s_setprio 1
	v_mfma_f32_16x16x32_bf16 v[118:121], v[162:165], v[178:181], v[118:121]
	v_mfma_f32_16x16x32_bf16 v[114:117], v[170:173], v[178:181], v[114:117]
	v_mfma_f32_16x16x32_bf16 v[102:105], v[162:165], v[186:189], v[102:105]
	v_mfma_f32_16x16x32_bf16 v[98:101], v[170:173], v[186:189], v[98:101]
	v_mfma_f32_16x16x32_bf16 v[86:89], v[162:165], v[208:211], v[86:89]
	v_mfma_f32_16x16x32_bf16 v[82:85], v[170:173], v[208:211], v[82:85]
	v_mfma_f32_16x16x32_bf16 v[70:73], v[162:165], v[216:219], v[70:73]
	v_mfma_f32_16x16x32_bf16 v[66:69], v[170:173], v[216:219], v[66:69]
	v_mfma_f32_16x16x32_bf16 v[118:121], v[166:169], v[182:185], v[118:121]
	v_mfma_f32_16x16x32_bf16 v[114:117], v[174:177], v[182:185], v[114:117]
	v_mfma_f32_16x16x32_bf16 v[102:105], v[166:169], v[204:207], v[102:105]
	v_mfma_f32_16x16x32_bf16 v[98:101], v[174:177], v[204:207], v[98:101]
	v_mfma_f32_16x16x32_bf16 v[86:89], v[166:169], v[212:215], v[86:89]
	v_mfma_f32_16x16x32_bf16 v[82:85], v[174:177], v[212:215], v[82:85]
	v_mfma_f32_16x16x32_bf16 v[70:73], v[166:169], v[226:229], v[70:73]
	v_mfma_f32_16x16x32_bf16 v[66:69], v[174:177], v[226:229], v[66:69]
	s_setprio 0
	s_barrier
	s_add_i32 s85, s85, s33
	v_lshl_add_u64 v[148:149], s[74:75], 0, v[190:191]
	s_mov_b32 m0, s85
	ds_read_b128 v[178:181], v153 offset:16384
	ds_read_b128 v[182:185], v153 offset:17408
	ds_read_b128 v[186:189], v153 offset:18432
	ds_read_b128 v[204:207], v153 offset:19456
	ds_read_b128 v[208:211], v153 offset:20480
	ds_read_b128 v[212:215], v153 offset:21504
	ds_read_b128 v[216:219], v153 offset:22528
	ds_read_b128 v[226:229], v153 offset:23552
	global_load_lds_dwordx4 v[148:149], off
	s_add_i32 m0, s85, 0x2000
	v_lshl_add_u64 v[220:221], s[74:75], 0, v[138:139]
	s_add_u32 s74, s74, s8
	s_addc_u32 s75, s75, s9
	s_add_i32 s85, s86, s33
	global_load_lds_dwordx4 v[220:221], off
	v_lshl_add_u64 v[230:231], s[74:75], 0, v[190:191]
	s_mov_b32 m0, s85
	v_lshl_add_u64 v[232:233], s[74:75], 0, v[138:139]
	global_load_lds_dwordx4 v[230:231], off
	s_add_i32 m0, s85, 0x2000
	v_lshl_add_u64 v[234:235], s[26:27], 0, v[134:135]
	global_load_lds_dwordx4 v[232:233], off
	s_mov_b32 m0, s34
	v_lshl_add_u64 v[236:237], s[26:27], 0, v[136:137]
	global_load_lds_dwordx4 v[234:235], off
	s_mov_b32 m0, s35
	s_nop 0
	global_load_lds_dwordx4 v[236:237], off
	s_waitcnt vmcnt(8)
	s_waitcnt lgkmcnt(0)
	s_barrier
	s_setprio 1
	s_waitcnt lgkmcnt(0)
	v_mfma_f32_16x16x32_bf16 v[62:65], v[130:133], v[178:181], v[62:65]
	v_mfma_f32_16x16x32_bf16 v[58:61], v[154:157], v[178:181], v[58:61]
	v_mfma_f32_16x16x32_bf16 v[46:49], v[130:133], v[186:189], v[46:49]
	v_mfma_f32_16x16x32_bf16 v[42:45], v[154:157], v[186:189], v[42:45]
	v_mfma_f32_16x16x32_bf16 v[30:33], v[130:133], v[208:211], v[30:33]
	v_mfma_f32_16x16x32_bf16 v[26:29], v[154:157], v[208:211], v[26:29]
	v_mfma_f32_16x16x32_bf16 v[14:17], v[130:133], v[216:219], v[14:17]
	v_mfma_f32_16x16x32_bf16 v[10:13], v[154:157], v[216:219], v[10:13]
	v_mfma_f32_16x16x32_bf16 v[62:65], v[144:147], v[182:185], v[62:65]
	v_mfma_f32_16x16x32_bf16 v[58:61], v[158:161], v[182:185], v[58:61]
	v_mfma_f32_16x16x32_bf16 v[46:49], v[144:147], v[204:207], v[46:49]
	v_mfma_f32_16x16x32_bf16 v[42:45], v[158:161], v[204:207], v[42:45]
	v_mfma_f32_16x16x32_bf16 v[30:33], v[144:147], v[212:215], v[30:33]
	v_mfma_f32_16x16x32_bf16 v[26:29], v[158:161], v[212:215], v[26:29]
	v_mfma_f32_16x16x32_bf16 v[14:17], v[144:147], v[226:229], v[14:17]
	v_mfma_f32_16x16x32_bf16 v[10:13], v[158:161], v[226:229], v[10:13]
	s_setprio 0
	s_setprio 1
	v_mfma_f32_16x16x32_bf16 v[54:57], v[162:165], v[178:181], v[54:57]
	v_mfma_f32_16x16x32_bf16 v[50:53], v[170:173], v[178:181], v[50:53]
	v_mfma_f32_16x16x32_bf16 v[38:41], v[162:165], v[186:189], v[38:41]
	v_mfma_f32_16x16x32_bf16 v[34:37], v[170:173], v[186:189], v[34:37]
	v_mfma_f32_16x16x32_bf16 v[22:25], v[162:165], v[208:211], v[22:25]
	v_mfma_f32_16x16x32_bf16 v[18:21], v[170:173], v[208:211], v[18:21]
	v_mfma_f32_16x16x32_bf16 v[6:9], v[162:165], v[216:219], v[6:9]
	v_mfma_f32_16x16x32_bf16 v[2:5], v[170:173], v[216:219], v[2:5]
	v_mfma_f32_16x16x32_bf16 v[54:57], v[166:169], v[182:185], v[54:57]
	v_mfma_f32_16x16x32_bf16 v[50:53], v[174:177], v[182:185], v[50:53]
	v_mfma_f32_16x16x32_bf16 v[38:41], v[166:169], v[204:207], v[38:41]
	v_mfma_f32_16x16x32_bf16 v[34:37], v[174:177], v[204:207], v[34:37]
	v_mfma_f32_16x16x32_bf16 v[22:25], v[166:169], v[212:215], v[22:25]
	v_mfma_f32_16x16x32_bf16 v[18:21], v[174:177], v[212:215], v[18:21]
	v_mfma_f32_16x16x32_bf16 v[6:9], v[166:169], v[226:229], v[6:9]
	v_mfma_f32_16x16x32_bf16 v[2:5], v[174:177], v[226:229], v[2:5]
	s_setprio 0
	s_barrier
	s_add_i32 s74, 0, 0x18000
	s_add_i32 s75, 0, 0x1c000
	v_add_u32_e32 v158, s74, v152
	v_add_u32_e32 v174, s75, v152
	ds_read_b128 v[130:133], v158
	ds_read_b128 v[144:147], v158 offset:1024
	ds_read_b128 v[154:157], v158 offset:2048
	ds_read_b128 v[158:161], v158 offset:3072
	ds_read_b128 v[162:165], v174
	ds_read_b128 v[166:169], v174 offset:1024
	ds_read_b128 v[170:173], v174 offset:2048
	ds_read_b128 v[174:177], v174 offset:3072
	s_add_u32 s26, s26, s8
	s_addc_u32 s27, s27, s9
	s_mov_b32 m0, s36
	v_lshl_add_u64 v[238:239], s[26:27], 0, v[134:135]
	ds_read_b128 v[178:181], v153 offset:32768
	ds_read_b128 v[182:185], v153 offset:33792
	ds_read_b128 v[186:189], v153 offset:34816
	ds_read_b128 v[204:207], v153 offset:35840
	ds_read_b128 v[208:211], v153 offset:36864
	ds_read_b128 v[212:215], v153 offset:37888
	ds_read_b128 v[216:219], v153 offset:38912
	ds_read_b128 v[226:229], v153 offset:39936
	global_load_lds_dwordx4 v[238:239], off
	v_lshl_add_u64 v[238:239], s[26:27], 0, v[136:137]
	s_mov_b32 m0, s37
	s_nop 0
	global_load_lds_dwordx4 v[238:239], off
	s_waitcnt vmcnt(8)
	s_waitcnt lgkmcnt(0)
	s_barrier
	s_setprio 1
	s_waitcnt lgkmcnt(0)
	v_mfma_f32_16x16x32_bf16 v[126:129], v[130:133], v[178:181], v[126:129]
	v_mfma_f32_16x16x32_bf16 v[122:125], v[154:157], v[178:181], v[122:125]
	v_mfma_f32_16x16x32_bf16 v[110:113], v[130:133], v[186:189], v[110:113]
	v_mfma_f32_16x16x32_bf16 v[106:109], v[154:157], v[186:189], v[106:109]
	v_mfma_f32_16x16x32_bf16 v[94:97], v[130:133], v[208:211], v[94:97]
	v_mfma_f32_16x16x32_bf16 v[90:93], v[154:157], v[208:211], v[90:93]
	v_mfma_f32_16x16x32_bf16 v[78:81], v[130:133], v[216:219], v[78:81]
	v_mfma_f32_16x16x32_bf16 v[74:77], v[154:157], v[216:219], v[74:77]
	v_mfma_f32_16x16x32_bf16 v[126:129], v[144:147], v[182:185], v[126:129]
	v_mfma_f32_16x16x32_bf16 v[122:125], v[158:161], v[182:185], v[122:125]
	v_mfma_f32_16x16x32_bf16 v[110:113], v[144:147], v[204:207], v[110:113]
	v_mfma_f32_16x16x32_bf16 v[106:109], v[158:161], v[204:207], v[106:109]
	v_mfma_f32_16x16x32_bf16 v[94:97], v[144:147], v[212:215], v[94:97]
	v_mfma_f32_16x16x32_bf16 v[90:93], v[158:161], v[212:215], v[90:93]
	v_mfma_f32_16x16x32_bf16 v[78:81], v[144:147], v[226:229], v[78:81]
	v_mfma_f32_16x16x32_bf16 v[74:77], v[158:161], v[226:229], v[74:77]
	s_setprio 0
	s_setprio 1
	v_mfma_f32_16x16x32_bf16 v[118:121], v[162:165], v[178:181], v[118:121]
	v_mfma_f32_16x16x32_bf16 v[114:117], v[170:173], v[178:181], v[114:117]
	v_mfma_f32_16x16x32_bf16 v[102:105], v[162:165], v[186:189], v[102:105]
	v_mfma_f32_16x16x32_bf16 v[98:101], v[170:173], v[186:189], v[98:101]
	v_mfma_f32_16x16x32_bf16 v[86:89], v[162:165], v[208:211], v[86:89]
	v_mfma_f32_16x16x32_bf16 v[82:85], v[170:173], v[208:211], v[82:85]
	v_mfma_f32_16x16x32_bf16 v[70:73], v[162:165], v[216:219], v[70:73]
	v_mfma_f32_16x16x32_bf16 v[66:69], v[170:173], v[216:219], v[66:69]
	v_mfma_f32_16x16x32_bf16 v[118:121], v[166:169], v[182:185], v[118:121]
	v_mfma_f32_16x16x32_bf16 v[114:117], v[174:177], v[182:185], v[114:117]
	v_mfma_f32_16x16x32_bf16 v[102:105], v[166:169], v[204:207], v[102:105]
	v_mfma_f32_16x16x32_bf16 v[98:101], v[174:177], v[204:207], v[98:101]
	v_mfma_f32_16x16x32_bf16 v[86:89], v[166:169], v[212:215], v[86:89]
	v_mfma_f32_16x16x32_bf16 v[82:85], v[174:177], v[212:215], v[82:85]
	v_mfma_f32_16x16x32_bf16 v[70:73], v[166:169], v[226:229], v[70:73]
	v_mfma_f32_16x16x32_bf16 v[66:69], v[174:177], v[226:229], v[66:69]
	s_setprio 0
	s_barrier
	s_add_i32 s26, s74, s33
	v_lshl_add_u64 v[148:149], v[148:149], 0, s[68:69]
	s_mov_b32 m0, s26
	ds_read_b128 v[178:181], v153 offset:49152
	ds_read_b128 v[182:185], v153 offset:50176
	ds_read_b128 v[186:189], v153 offset:51200
	ds_read_b128 v[204:207], v153 offset:52224
	ds_read_b128 v[208:211], v153 offset:53248
	ds_read_b128 v[212:215], v153 offset:54272
	ds_read_b128 v[216:219], v153 offset:55296
	ds_read_b128 v[226:229], v153 offset:56320
	global_load_lds_dwordx4 v[148:149], off
	v_lshl_add_u64 v[148:149], v[220:221], 0, s[68:69]
	s_add_i32 m0, s26, 0x2000
	s_add_i32 s26, s75, s33
	global_load_lds_dwordx4 v[148:149], off
	v_lshl_add_u64 v[148:149], v[230:231], 0, s[68:69]
	s_mov_b32 m0, s26
	s_nop 0
	global_load_lds_dwordx4 v[148:149], off
	v_lshl_add_u64 v[148:149], v[232:233], 0, s[68:69]
	s_add_i32 m0, s26, 0x2000
	s_nop 0
	global_load_lds_dwordx4 v[148:149], off
	v_lshl_add_u64 v[148:149], v[234:235], 0, s[68:69]
	s_mov_b32 m0, s59
	s_nop 0
	global_load_lds_dwordx4 v[148:149], off
	v_lshl_add_u64 v[148:149], v[236:237], 0, s[68:69]
	s_mov_b32 m0, s64
	s_nop 0
	global_load_lds_dwordx4 v[148:149], off
	s_waitcnt vmcnt(8)
	s_waitcnt lgkmcnt(0)
	s_barrier
	s_setprio 1
	s_waitcnt lgkmcnt(0)
	v_mfma_f32_16x16x32_bf16 v[62:65], v[130:133], v[178:181], v[62:65]
	v_mfma_f32_16x16x32_bf16 v[58:61], v[154:157], v[178:181], v[58:61]
	v_mfma_f32_16x16x32_bf16 v[46:49], v[130:133], v[186:189], v[46:49]
	v_mfma_f32_16x16x32_bf16 v[42:45], v[154:157], v[186:189], v[42:45]
	v_mfma_f32_16x16x32_bf16 v[30:33], v[130:133], v[208:211], v[30:33]
	v_mfma_f32_16x16x32_bf16 v[26:29], v[154:157], v[208:211], v[26:29]
	v_mfma_f32_16x16x32_bf16 v[14:17], v[130:133], v[216:219], v[14:17]
	v_mfma_f32_16x16x32_bf16 v[10:13], v[154:157], v[216:219], v[10:13]
	v_mfma_f32_16x16x32_bf16 v[62:65], v[144:147], v[182:185], v[62:65]
	v_mfma_f32_16x16x32_bf16 v[58:61], v[158:161], v[182:185], v[58:61]
	v_mfma_f32_16x16x32_bf16 v[46:49], v[144:147], v[204:207], v[46:49]
	v_mfma_f32_16x16x32_bf16 v[42:45], v[158:161], v[204:207], v[42:45]
	v_mfma_f32_16x16x32_bf16 v[30:33], v[144:147], v[212:215], v[30:33]
	v_mfma_f32_16x16x32_bf16 v[26:29], v[158:161], v[212:215], v[26:29]
	v_mfma_f32_16x16x32_bf16 v[14:17], v[144:147], v[226:229], v[14:17]
	v_mfma_f32_16x16x32_bf16 v[10:13], v[158:161], v[226:229], v[10:13]
	s_setprio 0
	s_setprio 1
	v_mfma_f32_16x16x32_bf16 v[54:57], v[162:165], v[178:181], v[54:57]
	v_mfma_f32_16x16x32_bf16 v[50:53], v[170:173], v[178:181], v[50:53]
	v_mfma_f32_16x16x32_bf16 v[38:41], v[162:165], v[186:189], v[38:41]
	v_mfma_f32_16x16x32_bf16 v[34:37], v[170:173], v[186:189], v[34:37]
	v_mfma_f32_16x16x32_bf16 v[22:25], v[162:165], v[208:211], v[22:25]
	v_mfma_f32_16x16x32_bf16 v[18:21], v[170:173], v[208:211], v[18:21]
	v_mfma_f32_16x16x32_bf16 v[6:9], v[162:165], v[216:219], v[6:9]
	v_mfma_f32_16x16x32_bf16 v[2:5], v[170:173], v[216:219], v[2:5]
	v_mfma_f32_16x16x32_bf16 v[54:57], v[166:169], v[182:185], v[54:57]
	v_mfma_f32_16x16x32_bf16 v[50:53], v[174:177], v[182:185], v[50:53]
	v_mfma_f32_16x16x32_bf16 v[38:41], v[166:169], v[204:207], v[38:41]
	v_mfma_f32_16x16x32_bf16 v[34:37], v[174:177], v[204:207], v[34:37]
	v_mfma_f32_16x16x32_bf16 v[22:25], v[166:169], v[212:215], v[22:25]
	v_mfma_f32_16x16x32_bf16 v[18:21], v[174:177], v[212:215], v[18:21]
	v_mfma_f32_16x16x32_bf16 v[6:9], v[166:169], v[226:229], v[6:9]
	v_mfma_f32_16x16x32_bf16 v[2:5], v[174:177], v[226:229], v[2:5]
	s_setprio 0
	s_add_u32 s24, s24, 0x100
	s_addc_u32 s25, s25, 0
	s_add_u32 s28, s28, 0x100
	s_addc_u32 s29, s29, 0
	s_cmp_ge_i32 s82, s81
	s_mov_b32 s26, s82
	s_barrier
	s_cbranch_scc0 .LBB0_1766
	s_and_b64 vcc, exec, s[14:15]
	s_cbranch_vccz .LBB0_1769
	s_barrier
